# stack22: stack21 + layer-1 input-projection weight conversion moved into layer-0 FFN-up tail (spare CUs)
# baseline (speedup 1.0000x reference)
.LBB0_8:
	v_readlane_b32 s26, v251, 1
	v_readlane_b32 s27, v251, 2
	s_load_dwordx2 s[96:97], s[26:27], 0x138
	v_readlane_b32 s30, v251, 0
	s_mov_b32 s21, s30
	v_mov_b32_e32 v22, v224
	s_waitcnt lgkmcnt(0)
	s_add_u32 s2, s96, 0x1c829800
	s_addc_u32 s3, s97, 0
	v_writelane_b32 v250, s2, 50
	s_mov_b32 s42, s4
	v_lshl_add_u32 v16, s30, 9, v22
	v_writelane_b32 v250, s3, 51
	s_lshl_b32 s2, s4, 10
	s_mov_b32 s4, 0x118000
	s_mov_b32 s3, s87
	v_cmp_gt_i32_e32 vcc, s4, v16
	s_and_saveexec_b64 s[4:5], vcc
	v_writelane_b32 v250, s26, 52
	s_nop 1
	v_writelane_b32 v250, s27, 53
	s_cbranch_execz .LBB0_49
	s_cmp_eq_u32 s42, 1
	s_cbranch_scc1 .LBB0_49
	s_load_dwordx4 s[12:15], s[26:27], 0x40
	s_mul_i32 s8, s42, 0x2210000
	s_mov_b64 s[6:7], 0
	v_lshlrev_b32_e32 v17, 1, v16
	v_mov_b32_e32 v23, v16
	s_waitcnt lgkmcnt(0)
	s_add_u32 s8, s14, s8
	s_addc_u32 s9, s15, 0
	s_lshl_b64 s[10:11], s[2:3], 2
	s_add_u32 s10, s12, s10
	s_addc_u32 s11, s13, s11
	s_cmp_lg_u64 s[12:13], 0
	s_cselect_b64 s[12:13], -1, 0
	s_branch .LBB0_12

.Lkvh_done:
	v_readlane_b32 s37, v250, 58
	s_cmp_lg_u32 s37, 0
	s_cbranch_scc1 .Lwi_done
	s_cmp_gt_u32 s90, 44
	s_cselect_b32 s36, 44, 0
	s_cmp_lt_u32 s21, s36
	s_cbranch_scc1 .Lwi_done
	v_readlane_b32 s40, v250, 52
	v_readlane_b32 s41, v250, 53
	v_readfirstlane_b32 s34, v224
	v_and_b32_e32 v0, 63, v224
	s_lshr_b32 s34, s34, 6
	s_sub_u32 s35, s21, s36
	s_lshl_b32 s35, s35, 3
	s_add_u32 s34, s34, s35
	s_sub_u32 s35, s90, s36
	s_lshl_b32 s35, s35, 3
	s_load_dwordx4 s[44:47], s[40:41], 0x40
	v_lshlrev_b32_e32 v1, 2, v0
	v_add_u32_e32 v2, 0x8840, v1
	v_add_u32_e32 v3, 0x11080, v1
	v_add_u32_e32 v4, 0x198c0, v1
	v_add_u32_e32 v5, 0x22100, v1
	v_add_u32_e32 v6, 0x2a940, v1
	v_add_u32_e32 v7, 0x33180, v1
	v_add_u32_e32 v8, 0x3b9c0, v1
	v_lshlrev_b32_e32 v9, 11, v0
	v_lshrrev_b32_e32 v10, 5, v0
	v_lshl_add_u32 v10, v10, 5, v0
	v_lshlrev_b32_e32 v10, 2, v10
	v_add_u32_e32 v11, 0x8840, v10
	v_add_u32_e32 v12, 0x11080, v10
	v_add_u32_e32 v13, 0x198c0, v10
	v_add_u32_e32 v14, 0x22100, v10
	v_add_u32_e32 v15, 0x2a940, v10
	v_add_u32_e32 v16, 0x33180, v10
	v_add_u32_e32 v17, 0x3b9c0, v10
	s_add_u32 s42, s96, 0x1c829800
	s_addc_u32 s43, s97, 0
	s_waitcnt lgkmcnt(0)
	s_add_u32 s46, s46, 0x2210000
	s_addc_u32 s47, s47, 0
	s_add_u32 s44, s44, 0x1000
	s_addc_u32 s45, s45, 0
	s_mov_b32 s48, s34
.Lwi_loop:
	s_cmp_ge_u32 s48, 0x4600
	s_cbranch_scc1 .Lwi_done
	s_mul_hi_u32 s49, s48, 0x1d41d42
	s_mul_i32 s56, s49, 0x8c
	s_sub_u32 s56, s48, s56
	s_lshr_b32 s57, s56, 2
	s_and_b32 s62, s56, 3
	s_lshl_b32 s62, s62, 6
	s_lshl_b32 s58, s56, 6
	s_mov_b32 s37, 0
	s_cmp_lt_u32 s57, 10
	s_cbranch_scc1 .Lwi_map_done
	s_cmp_lt_u32 s57, 12
	s_cbranch_scc1 .Lwi_map_p16
	s_cmp_lt_u32 s57, 16
	s_cbranch_scc1 .Lwi_map_perm
	s_cmp_lt_u32 s57, 18
	s_cbranch_scc1 .Lwi_map_p16
	s_cmp_eq_u32 s57, 18
	s_cbranch_scc1 .Lwi_map_code
	s_sub_u32 s58, s58, 0xf0
	s_branch .Lwi_map_done
.Lwi_map_p16:
	s_add_u32 s58, s58, 16
	s_branch .Lwi_map_done
.Lwi_map_perm:
	s_cmp_lt_u32 s57, 14
	s_movk_i32 s59, 0xe10
	s_cselect_b32 s58, 0xc10, s59
	s_and_b32 s59, s57, 1
	s_lshl_b32 s59, s59, 8
	s_add_u32 s58, s58, s59
	s_lshr_b32 s59, s62, 5
	s_and_b32 s59, s59, 3
	s_lshl_b32 s59, s59, 6
	s_add_u32 s58, s58, s59
	s_lshr_b32 s59, s62, 7
	s_lshl_b32 s59, s59, 5
	s_add_u32 s58, s58, s59
	s_mov_b32 s37, 1
	s_branch .Lwi_map_done
.Lwi_map_code:
	s_movk_i32 s58, 0xa00
	s_mov_b32 s37, 2
.Lwi_map_done:
	s_mul_i32 s59, s49, 0x44200
	s_lshl_b32 s58, s58, 2
	s_add_u32 s59, s59, s58
	s_add_u32 s58, s46, s59
	s_addc_u32 s59, s47, 0
	s_cmp_eq_u32 s37, 1
	s_cbranch_scc1 .Lwi_ld_perm
	global_load_dword v32, v1, s[58:59]
	global_load_dword v33, v2, s[58:59]
	global_load_dword v34, v3, s[58:59]
	global_load_dword v35, v4, s[58:59]
	global_load_dword v36, v5, s[58:59]
	global_load_dword v37, v6, s[58:59]
	global_load_dword v38, v7, s[58:59]
	global_load_dword v39, v8, s[58:59]
	s_branch .Lwi_ld_done
.Lwi_ld_perm:
	global_load_dword v32, v10, s[58:59]
	global_load_dword v33, v11, s[58:59]
	global_load_dword v34, v12, s[58:59]
	global_load_dword v35, v13, s[58:59]
	global_load_dword v36, v14, s[58:59]
	global_load_dword v37, v15, s[58:59]
	global_load_dword v38, v16, s[58:59]
	global_load_dword v39, v17, s[58:59]
.Lwi_ld_done:
	s_lshl_b32 s60, s49, 5
	s_add_u32 s60, s44, s60
	s_addc_u32 s61, s45, 0
	global_load_dwordx4 v[24:27], v177, s[60:61]
	global_load_dwordx4 v[28:31], v177, s[60:61] offset:16
	s_lshl_b32 s60, s56, 17
	s_lshl_b32 s61, s49, 4
	s_add_u32 s60, s60, s61
	s_add_u32 s60, s42, s60
	s_addc_u32 s61, s43, 0
	s_waitcnt vmcnt(0)
	v_mul_f32_e32 v32, v32, v24
	v_mul_f32_e32 v33, v33, v25
	v_mul_f32_e32 v34, v34, v26
	v_mul_f32_e32 v35, v35, v27
	v_mul_f32_e32 v36, v36, v28
	v_mul_f32_e32 v37, v37, v29
	v_mul_f32_e32 v38, v38, v30
	v_mul_f32_e32 v39, v39, v31
	v_cvt_pk_bf16_f32 v32, v32, v33
	v_cvt_pk_bf16_f32 v33, v34, v35
	v_cvt_pk_bf16_f32 v34, v36, v37
	v_cvt_pk_bf16_f32 v35, v38, v39
	s_cmp_lg_u32 s37, 2
	s_cbranch_scc1 .Lwi_st
	s_sub_u32 s62, 16, s62
	s_max_i32 s62, s62, 0
	v_cmp_gt_u32_e32 vcc, s62, v0
	v_cndmask_b32_e32 v32, 0, v32, vcc
	v_cndmask_b32_e32 v33, 0, v33, vcc
	v_cndmask_b32_e32 v34, 0, v34, vcc
	v_cndmask_b32_e32 v35, 0, v35, vcc
.Lwi_st:
	global_store_dwordx4 v9, v[32:35], s[60:61]
	s_add_u32 s48, s48, s35
	s_branch .Lwi_loop
